# sample attention: the conversion pass's f32-stage LDS reads are issued between the P.V MFMAs (into registers freed by each MFMA pair)
# speedup vs baseline: 1.0189x; 1.0062x over previous
.Lsa_pdone:
	s_or_b64 exec, exec, s[24:25]
	v_add_u32_e32 v40, 0xec00, v221
	s_waitcnt lgkmcnt(0)
	s_barrier
	ds_read2_b32 v[202:203], v40 offset0:52 offset1:84
	ds_read_b64_tr_b16 v[226:227], v43
	ds_read_b64_tr_b16 v[228:229], v44
	ds_read_b64_tr_b16 v[186:187], v43 offset:4096
	ds_read_b64_tr_b16 v[188:189], v44 offset:4096
	ds_read_b64_tr_b16 v[182:183], v43 offset:8192
	ds_read_b64_tr_b16 v[184:185], v44 offset:8192
	ds_read_b64_tr_b16 v[178:179], v43 offset:12288
	ds_read_b64_tr_b16 v[180:181], v44 offset:12288
	s_waitcnt lgkmcnt(8)
	v_pk_mul_f32 v[2:3], v[202:203], v[2:3] op_sel_hi:[0,1]
	v_pk_mul_f32 v[4:5], v[202:203], v[4:5] op_sel_hi:[0,1]
	v_pk_mul_f32 v[6:7], v[202:203], v[6:7] op_sel_hi:[0,1]
	v_pk_mul_f32 v[8:9], v[202:203], v[8:9] op_sel_hi:[0,1]
	v_pk_mul_f32 v[10:11], v[202:203], v[10:11] op_sel_hi:[0,1]
	v_pk_mul_f32 v[12:13], v[202:203], v[12:13] op_sel_hi:[0,1]
	v_pk_mul_f32 v[14:15], v[202:203], v[14:15] op_sel_hi:[0,1]
	v_pk_mul_f32 v[16:17], v[202:203], v[16:17] op_sel_hi:[0,1]
	v_pk_mul_f32 v[18:19], v[202:203], v[18:19] op_sel:[1,0]
	v_pk_mul_f32 v[20:21], v[202:203], v[20:21] op_sel:[1,0]
	v_pk_mul_f32 v[22:23], v[202:203], v[22:23] op_sel:[1,0]
	v_pk_mul_f32 v[24:25], v[202:203], v[24:25] op_sel:[1,0]
	v_pk_mul_f32 v[26:27], v[202:203], v[26:27] op_sel:[1,0]
	v_pk_mul_f32 v[28:29], v[202:203], v[28:29] op_sel:[1,0]
	v_pk_mul_f32 v[30:31], v[202:203], v[30:31] op_sel:[1,0]
	v_pk_mul_f32 v[32:33], v[202:203], v[32:33] op_sel:[1,0]
	s_waitcnt lgkmcnt(4)
	ds_read_b128 v[230:233], v222 offset:37888
	ds_read_b128 v[234:237], v222 offset:42496
	ds_read_b128 v[238:241], v222 offset:37920
	ds_read_b128 v[242:245], v222 offset:42528
	ds_read_b128 v[246:249], v222 offset:37952
	ds_read_b128 v[206:209], v222 offset:42560
	ds_read_b128 v[34:37], v222 offset:37984
	ds_read_b128 v[38:41], v222 offset:42592
	v_lshrrev_b32_e32 v202, 3, v0
	v_bfe_u32 v203, v0, 5, 1
	v_and_or_b32 v202, v202, s28, v203
	v_lshlrev_b32_e32 v203, 5, v0
	v_and_b32_e32 v203, 0x3e0, v203
	v_lshlrev_b32_e32 v202, 10, v202
	v_add3_u32 v42, 0, v203, v202
	v_add_u32_e32 v45, 0xf400, v42
	v_lshlrev_b32_e32 v202, 4, v0
	v_and_b32_e32 v203, 0xffffff80, v202
	v_and_b32_e32 v202, 0x70, v202
	v_add3_u32 v205, s38, v203, v202
	s_and_b64 vcc, exec, s[18:19]
	s_waitcnt lgkmcnt(0)
	s_barrier
	v_mfma_f32_32x32x16_bf16 v[2:17], v[226:229], v[230:233], v[2:17]
	v_mfma_f32_32x32x16_bf16 v[18:33], v[226:229], v[234:237], v[18:33]
	s_cbranch_vccnz .Lsa_cv0
	s_waitcnt vmcnt(0)
	ds_read_b128 v[226:229], v42 offset:64512
	ds_read_b128 v[230:233], v42 offset:64528
	ds_read_b128 v[234:237], v45 offset:4096
.Lsa_cv0:
	v_mfma_f32_32x32x16_bf16 v[2:17], v[186:189], v[238:241], v[2:17]
	v_mfma_f32_32x32x16_bf16 v[18:33], v[186:189], v[242:245], v[18:33]
	s_cbranch_vccnz .Lsa_cv1
	ds_read_b128 v[238:241], v45 offset:4112
	ds_read_b128 v[242:245], v45 offset:6144
.Lsa_cv1:
	v_mfma_f32_32x32x16_bf16 v[2:17], v[182:185], v[246:249], v[2:17]
	v_mfma_f32_32x32x16_bf16 v[18:33], v[182:185], v[206:209], v[18:33]
	s_cbranch_vccnz .Lsa_cv2
	ds_read_b128 v[246:249], v45 offset:6160
.Lsa_cv2:
	v_mfma_f32_32x32x16_bf16 v[2:17], v[178:181], v[34:37], v[2:17]
	v_mfma_f32_32x32x16_bf16 v[18:33], v[178:181], v[38:41], v[18:33]
	s_cbranch_vccnz .Lsa_cv3
	ds_read_b128 v[34:37], v42 offset:62464
	ds_read_b128 v[38:41], v42 offset:62480
	ds_read_b128 v[178:181], v205
.Lsa_cv3:
	s_cmp_lt_u32 s41, s37
	s_cbranch_scc0 .LBB0_828
	s_mov_b64 s[10:11], -1
	s_and_b64 vcc, exec, s[18:19]
	s_cbranch_vccz .LBB0_825
	s_waitcnt lgkmcnt(0)
	s_and_saveexec_b64 s[18:19], s[12:13]
	s_cbranch_execz .LBB0_824
	s_mov_b64 s[20:21], 0
	v_mov_b32_e32 v40, v250
	s_branch .LBB0_818

.LBB0_825:
	s_andn2_b64 vcc, exec, s[10:11]
	s_cbranch_vccnz .LBB0_827
	s_waitcnt lgkmcnt(0)
	v_cvt_pk_bf16_f32 v34, v34, v35
	v_cvt_pk_bf16_f32 v35, v36, v37
	v_cvt_pk_bf16_f32 v36, v38, v39
	v_cvt_pk_bf16_f32 v37, v40, v41
	v_cvt_pk_bf16_f32 v226, v226, v227
	v_cvt_pk_bf16_f32 v227, v228, v229
	v_cvt_pk_bf16_f32 v228, v230, v231
	v_cvt_pk_bf16_f32 v229, v232, v233
	v_cvt_pk_bf16_f32 v234, v234, v235
	v_cvt_pk_bf16_f32 v235, v236, v237
	v_cvt_pk_bf16_f32 v236, v238, v239
	v_cvt_pk_bf16_f32 v237, v240, v241
	v_cvt_pk_bf16_f32 v242, v242, v243
	v_cvt_pk_bf16_f32 v243, v244, v245
	v_cvt_pk_bf16_f32 v244, v246, v247
	v_cvt_pk_bf16_f32 v245, v248, v249
	s_waitcnt lgkmcnt(0)
	v_cvt_pk_bf16_f32 v178, v178, v179
	v_cvt_pk_bf16_f32 v179, v180, v181
	v_mov_b32_e32 v180, v0
	s_nop 0
	v_ashrrev_i32_e32 v181, 3, v180
	v_bfe_u32 v183, v180, 5, 1
	v_lshrrev_b32_e32 v188, 2, v181
	v_and_b32_e32 v182, -8, v181
	v_lshlrev_b32_e32 v184, 10, v180
	v_and_b32_e32 v185, 15, v180
	v_and_b32_e32 v188, 2, v188
	v_lshlrev_b32_e32 v189, 2, v183
	v_and_b32_e32 v184, 0x4000, v184
	v_or_b32_e32 v186, v182, v183
	v_bitop3_b32 v202, v189, v185, v188 bitop3:0x36
	v_add_u32_e32 v184, 0, v184
	v_lshlrev_b32_e32 v187, 8, v186
	v_lshlrev_b32_e32 v202, 4, v202
	v_add3_u32 v187, v184, v202, v187
	ds_write_b128 v187, v[34:37]
	v_or_b32_e32 v34, 2, v186
	v_lshlrev_b32_e32 v35, 8, v34
	v_lshlrev_b32_e32 v34, 2, v34
	v_and_b32_e32 v34, 12, v34
	v_bitop3_b32 v34, v34, v185, v188 bitop3:0x36
	v_lshlrev_b32_e32 v34, 4, v34
	v_add3_u32 v34, v184, v34, v35
	ds_write_b128 v34, v[226:229]
	v_or_b32_e32 v34, 4, v182
	v_or_b32_e32 v35, v34, v183
	v_bfe_u32 v34, v34, 2, 2
	v_bitop3_b32 v34, v189, v185, v34 bitop3:0x36
	v_lshlrev_b32_e32 v35, 8, v35
	v_lshlrev_b32_e32 v34, 4, v34
	v_add3_u32 v34, v184, v34, v35
	ds_write_b128 v34, v[234:237]
	v_or_b32_e32 v34, 6, v182
	v_or_b32_e32 v35, v34, v183
	v_lshlrev_b32_e32 v36, 8, v35
	v_lshlrev_b32_e32 v35, 2, v35
	v_and_b32_e32 v35, 12, v35
	v_bfe_u32 v34, v34, 2, 2
	v_bitop3_b32 v34, v35, v185, v34 bitop3:0x36
	v_lshlrev_b32_e32 v34, 4, v34
	v_add3_u32 v34, v184, v34, v36
	ds_write_b128 v34, v[242:245]
	v_lshlrev_b32_e32 v34, 2, v180
	v_and_b32_e32 v34, 28, v34
	v_mad_u64_u32 v[34:35], s[10:11], v181, 40, v[34:35]
	v_lshl_add_u32 v34, v34, 1, 0
	ds_write_b64 v34, v[178:179] offset:32768
